# phase A: add hand-written rmsnorm row loop with 6 rows in flight per wave (on top of pipelined transposes)
# baseline (speedup 1.0000x reference)
; __device__ __forceinline__ u32x2 pack4(f32x4 v) { u32x2 r; r.x = cvt_pk(v[0], v[1]); r.y = cvt_pk(v[2], v[3]); return r; }
; __device__ __forceinline__ void phaseA(const Params& p, const int wv, const int rep) {
;     ...
;   const int gw = blockIdx.x * 8 + wid, nw = gridDim.x * 8;
;   u16* XN = (u16*)((char*)p.out + OOFF_XN);
;   u16* MN = (u16*)(ws + OFF_MN);
;   {
;     const int rend = (T + 2048) * rep;
;     auto rowsrc = [&](int r_) -> const float* {
;       const int r = r_ >= T + 2048 ? r_ - (T + 2048) : r_;
;       return r < TP ? p.in[0] + (size_t)r * 1024 : r < T ? p.in[1] + (size_t)(r - TP) * 1024 : p.in[2] + (size_t)(r - T) * 1024;
;     };
;     int r_ = gw;
;     f32x4 v[4];
;     if (r_ < rend) { const float* x = rowsrc(r_);
; #pragma unroll
;       for (int i = 0; i < 4; ++i) v[i] = *(const f32x4*)(x + (i * 64 + lane) * 4); }
;     while (r_ < rend) {
;       const int rn = r_ + nw;
;       f32x4 vn[4] = {v[0], v[1], v[2], v[3]};
;       if (rn < rend) { const float* x = rowsrc(rn);
; #pragma unroll
;         for (int i = 0; i < 4; ++i) vn[i] = *(const f32x4*)(x + (i * 64 + lane) * 4); }
;       const int r = r_ >= T + 2048 ? r_ - (T + 2048) : r_;
;       const float* w = r < T ? p.in[7] : p.in[19];
;       u16* dst = r < T ? XN + (size_t)r * 1024 : MN + (size_t)(r - T) * 1024;
;       float ss = 0.f;
; #pragma unroll
;       for (int i = 0; i < 4; ++i) ss += v[i][0] * v[i][0] + v[i][1] * v[i][1] + v[i][2] * v[i][2] + v[i][3] * v[i][3];
;       ss = wave_sum(ss);
;       const float rstd = rsqrtf(ss * (1.f / 1024.f) + EPS);
; #pragma unroll
;       for (int i = 0; i < 4; ++i) { f32x4 wv4 = *(const f32x4*)(w + (i * 64 + lane) * 4); *(u32x2*)(dst + (i * 64 + lane) * 4) = pack4(v[i] * rstd * wv4); }
; #pragma unroll
;       for (int i = 0; i < 4; ++i) v[i] = vn[i];
;       r_ = rn;
;     }
.LBB0_88:
	s_lshr_b32 s83, s81, 6
	s_lshl_b32 s29, s1, 3
	v_readlane_b32 s0, v251, 1
	s_add_i32 s2, s83, s29
	s_lshl_b32 s0, s0, 3
	v_writelane_b32 v251, s0, 54
	s_add_u32 s54, s50, 0x2620000
	s_addc_u32 s55, s51, 0
	v_writelane_b32 v251, s1, 55
	v_readlane_b32 s20, v251, 1
	s_nop 3
	s_cmpk_lg_u32 s20, 0x100
	s_cbranch_scc1 .Lrn_skip
	s_cmpk_lg_u32 s33, 1
	s_cbranch_scc1 .Lrn_skip
	v_readlane_b32 s8, v251, 6
	v_readlane_b32 s9, v251, 7
	v_readlane_b32 s10, v251, 8
	v_readlane_b32 s11, v251, 9
	v_readlane_b32 s12, v251, 10
	v_readlane_b32 s13, v251, 11
	v_readlane_b32 s14, v251, 20
	v_readlane_b32 s15, v251, 21
	v_readlane_b32 s16, v251, 28
	v_readlane_b32 s17, v251, 29
	s_add_u32 s18, s50, 0x2620000
	s_addc_u32 s19, s51, 0
	v_lshlrev_b32_e32 v68, 4, v24
	v_lshlrev_b32_e32 v69, 3, v24
	v_lshlrev_b32_e32 v220, 2, v24
	v_xor_b32_e32 v70, 0x80, v220
	v_xor_b32_e32 v71, 0x40, v220
	v_xor_b32_e32 v72, 0x20, v220
	v_xor_b32_e32 v73, 0x10, v220
	v_xor_b32_e32 v74, 0x8, v220
	v_xor_b32_e32 v75, 0x4, v220
	v_mov_b32_e32 v240, 0x358637bd
	s_nop 1
	global_load_dwordx4 v[76:79], v68, s[14:15]
	global_load_dwordx4 v[92:95], v68, s[16:17]
	global_load_dwordx4 v[80:83], v68, s[14:15] offset:1024
	global_load_dwordx4 v[96:99], v68, s[16:17] offset:1024
	global_load_dwordx4 v[84:87], v68, s[14:15] offset:2048
	global_load_dwordx4 v[100:103], v68, s[16:17] offset:2048
	global_load_dwordx4 v[88:91], v68, s[14:15] offset:3072
	global_load_dwordx4 v[104:107], v68, s[16:17] offset:3072
	s_add_u32 s20, s2, 0
	s_lshl_b32 s21, s20, 12
	s_add_u32 s24, s8, s21
	s_addc_u32 s25, s9, 0
	s_lshl_b32 s21, s20, 11
	s_add_u32 s72, s48, s21
	s_addc_u32 s73, s49, 0
	global_load_dwordx4 v[108:111], v68, s[24:25]
	global_load_dwordx4 v[112:115], v68, s[24:25] offset:1024
	global_load_dwordx4 v[116:119], v68, s[24:25] offset:2048
	global_load_dwordx4 v[120:123], v68, s[24:25] offset:3072
	s_add_u32 s20, s2, 2048
	s_lshl_b32 s21, s20, 12
	s_add_u32 s24, s8, s21
	s_addc_u32 s25, s9, 0
	s_lshl_b32 s21, s20, 11
	s_add_u32 s74, s48, s21
	s_addc_u32 s75, s49, 0
	global_load_dwordx4 v[124:127], v68, s[24:25]
	global_load_dwordx4 v[128:131], v68, s[24:25] offset:1024
	global_load_dwordx4 v[132:135], v68, s[24:25] offset:2048
	global_load_dwordx4 v[136:139], v68, s[24:25] offset:3072
	s_add_u32 s20, s2, 4096
	s_lshl_b32 s21, s20, 12
	s_add_u32 s24, s8, s21
	s_addc_u32 s25, s9, 0
	s_lshl_b32 s21, s20, 11
	s_add_u32 s76, s48, s21
	s_addc_u32 s77, s49, 0
	global_load_dwordx4 v[140:143], v68, s[24:25]
	global_load_dwordx4 v[144:147], v68, s[24:25] offset:1024
	global_load_dwordx4 v[148:151], v68, s[24:25] offset:2048
	global_load_dwordx4 v[152:155], v68, s[24:25] offset:3072
	s_add_u32 s20, s2, 6144
	s_lshl_b32 s21, s20, 12
	s_add_u32 s24, s8, s21
	s_addc_u32 s25, s9, 0
	s_lshl_b32 s21, s20, 11
	s_add_u32 s78, s48, s21
	s_addc_u32 s79, s49, 0
	global_load_dwordx4 v[156:159], v68, s[24:25]
	global_load_dwordx4 v[160:163], v68, s[24:25] offset:1024
	global_load_dwordx4 v[164:167], v68, s[24:25] offset:2048
	global_load_dwordx4 v[168:171], v68, s[24:25] offset:3072
	s_add_u32 s20, s2, 8192
	s_lshl_b32 s21, s20, 12
	s_add_u32 s24, s8, s21
	s_addc_u32 s25, s9, 0
	s_lshl_b32 s21, s20, 11
	s_add_u32 s84, s48, s21
	s_addc_u32 s85, s49, 0
	global_load_dwordx4 v[172:175], v68, s[24:25]
	global_load_dwordx4 v[176:179], v68, s[24:25] offset:1024
	global_load_dwordx4 v[180:183], v68, s[24:25] offset:2048
	global_load_dwordx4 v[184:187], v68, s[24:25] offset:3072
	s_add_u32 s20, s2, 10240
	s_lshl_b32 s21, s20, 12
	s_add_u32 s24, s8, s21
	s_addc_u32 s25, s9, 0
	s_lshl_b32 s21, s20, 11
	s_add_u32 s86, s48, s21
	s_addc_u32 s87, s49, 0
	global_load_dwordx4 v[188:191], v68, s[24:25]
	global_load_dwordx4 v[192:195], v68, s[24:25] offset:1024
	global_load_dwordx4 v[196:199], v68, s[24:25] offset:2048
	global_load_dwordx4 v[200:203], v68, s[24:25] offset:3072
	s_waitcnt vmcnt(20)
	v_pk_mul_f32 v[204:205], v[108:109], v[108:109]
	v_pk_mul_f32 v[206:207], v[110:111], v[110:111]
	v_pk_mul_f32 v[208:209], v[112:113], v[112:113]
	v_pk_mul_f32 v[210:211], v[114:115], v[114:115]
	v_pk_mul_f32 v[212:213], v[116:117], v[116:117]
	v_pk_mul_f32 v[214:215], v[118:119], v[118:119]
	v_pk_mul_f32 v[216:217], v[120:121], v[120:121]
	v_pk_mul_f32 v[218:219], v[122:123], v[122:123]
	v_add_f32_e32 v220, v204, v205
	v_add_f32_e32 v220, v206, v220
	v_add_f32_e32 v220, v207, v220
	v_add_f32_e32 v221, v208, v209
	v_add_f32_e32 v221, v210, v221
	v_add_f32_e32 v221, v211, v221
	v_add_f32_e32 v222, v212, v213
	v_add_f32_e32 v222, v214, v222
	v_add_f32_e32 v222, v215, v222
	v_add_f32_e32 v223, v216, v217
	v_add_f32_e32 v223, v218, v223
	v_add_f32_e32 v223, v219, v223
	v_add_f32_e32 v224, v220, v221
	v_add_f32_e32 v224, v222, v224
	v_add_f32_e32 v224, v223, v224
	ds_bpermute_b32 v225, v70, v224
	s_waitcnt lgkmcnt(0)
	v_add_f32_e32 v224, v224, v225
	ds_bpermute_b32 v225, v71, v224
	s_waitcnt lgkmcnt(0)
	v_add_f32_e32 v224, v224, v225
	ds_bpermute_b32 v225, v72, v224
	s_waitcnt lgkmcnt(0)
	v_add_f32_e32 v224, v224, v225
	ds_bpermute_b32 v225, v73, v224
	s_waitcnt lgkmcnt(0)
	v_add_f32_e32 v224, v224, v225
	ds_bpermute_b32 v225, v74, v224
	s_waitcnt lgkmcnt(0)
	v_add_f32_e32 v224, v224, v225
	ds_bpermute_b32 v225, v75, v224
	s_waitcnt lgkmcnt(0)
; __device__ __forceinline__ u32x2 pack4(f32x4 v) { u32x2 r; r.x = cvt_pk(v[0], v[1]); r.y = cvt_pk(v[2], v[3]); return r; }
; __device__ __forceinline__ void phaseA(const Params& p, const int wv, const int rep) {
;     ...
;       float ss = 0.f;
; #pragma unroll
;       for (int i = 0; i < 4; ++i) ss += v[i][0] * v[i][0] + v[i][1] * v[i][1] + v[i][2] * v[i][2] + v[i][3] * v[i][3];
;       ss = wave_sum(ss);
;       const float rstd = rsqrtf(ss * (1.f / 1024.f) + EPS);
; #pragma unroll
;       for (int i = 0; i < 4; ++i) { f32x4 wv4 = *(const f32x4*)(w + (i * 64 + lane) * 4); *(u32x2*)(dst + (i * 64 + lane) * 4) = pack4(v[i] * rstd * wv4); }
; #pragma unroll
;       for (int i = 0; i < 4; ++i) v[i] = vn[i];
;       r_ = rn;
	v_add_f32_e32 v224, v224, v225
	v_fmamk_f32 v224, v224, 0x3a800000, v240
	v_mul_f32_e32 v225, 0x4b800000, v224
	v_cmp_gt_f32_e32 vcc, 0x800000, v224
	s_nop 1
	v_cndmask_b32_e32 v224, v224, v225, vcc
	v_rsq_f32_e32 v224, v224
	s_nop 0
	v_mul_f32_e32 v225, 0x45800000, v224
	v_cndmask_b32_e32 v226, v224, v225, vcc
	v_pk_mul_f32 v[108:109], v[108:109], v[226:227] op_sel_hi:[1,0]
	v_pk_mul_f32 v[110:111], v[110:111], v[226:227] op_sel_hi:[1,0]
	v_pk_mul_f32 v[108:109], v[76:77], v[108:109]
	v_pk_mul_f32 v[110:111], v[78:79], v[110:111]
	v_cvt_pk_bf16_f32 v228, v108, v109
	v_cvt_pk_bf16_f32 v229, v110, v111
	v_pk_mul_f32 v[112:113], v[112:113], v[226:227] op_sel_hi:[1,0]
	v_pk_mul_f32 v[114:115], v[114:115], v[226:227] op_sel_hi:[1,0]
	v_pk_mul_f32 v[112:113], v[80:81], v[112:113]
	v_pk_mul_f32 v[114:115], v[82:83], v[114:115]
	v_cvt_pk_bf16_f32 v230, v112, v113
	v_cvt_pk_bf16_f32 v231, v114, v115
	v_pk_mul_f32 v[116:117], v[116:117], v[226:227] op_sel_hi:[1,0]
	v_pk_mul_f32 v[118:119], v[118:119], v[226:227] op_sel_hi:[1,0]
	v_pk_mul_f32 v[116:117], v[84:85], v[116:117]
	v_pk_mul_f32 v[118:119], v[86:87], v[118:119]
	v_cvt_pk_bf16_f32 v232, v116, v117
	v_cvt_pk_bf16_f32 v233, v118, v119
	v_pk_mul_f32 v[120:121], v[120:121], v[226:227] op_sel_hi:[1,0]
	v_pk_mul_f32 v[122:123], v[122:123], v[226:227] op_sel_hi:[1,0]
	v_pk_mul_f32 v[120:121], v[88:89], v[120:121]
	v_pk_mul_f32 v[122:123], v[90:91], v[122:123]
	v_cvt_pk_bf16_f32 v234, v120, v121
	v_cvt_pk_bf16_f32 v235, v122, v123
	global_store_dwordx2 v69, v[228:229], s[72:73]
	global_store_dwordx2 v69, v[230:231], s[72:73] offset:512
	global_store_dwordx2 v69, v[232:233], s[72:73] offset:1024
	global_store_dwordx2 v69, v[234:235], s[72:73] offset:1536
	s_add_u32 s20, s2, 12288
	s_lshl_b32 s21, s20, 12
	s_add_u32 s24, s8, s21
	s_addc_u32 s25, s9, 0
	s_lshl_b32 s21, s20, 11
	s_add_u32 s72, s48, s21
	s_addc_u32 s73, s49, 0
	global_load_dwordx4 v[108:111], v68, s[24:25]
	global_load_dwordx4 v[112:115], v68, s[24:25] offset:1024
	global_load_dwordx4 v[116:119], v68, s[24:25] offset:2048
	global_load_dwordx4 v[120:123], v68, s[24:25] offset:3072
	s_waitcnt vmcnt(24)
	v_pk_mul_f32 v[204:205], v[124:125], v[124:125]
	v_pk_mul_f32 v[206:207], v[126:127], v[126:127]
	v_pk_mul_f32 v[208:209], v[128:129], v[128:129]
	v_pk_mul_f32 v[210:211], v[130:131], v[130:131]
	v_pk_mul_f32 v[212:213], v[132:133], v[132:133]
	v_pk_mul_f32 v[214:215], v[134:135], v[134:135]
	v_pk_mul_f32 v[216:217], v[136:137], v[136:137]
	v_pk_mul_f32 v[218:219], v[138:139], v[138:139]
	v_add_f32_e32 v220, v204, v205
	v_add_f32_e32 v220, v206, v220
	v_add_f32_e32 v220, v207, v220
	v_add_f32_e32 v221, v208, v209
	v_add_f32_e32 v221, v210, v221
	v_add_f32_e32 v221, v211, v221
	v_add_f32_e32 v222, v212, v213
	v_add_f32_e32 v222, v214, v222
	v_add_f32_e32 v222, v215, v222
	v_add_f32_e32 v223, v216, v217
	v_add_f32_e32 v223, v218, v223
	v_add_f32_e32 v223, v219, v223
	v_add_f32_e32 v224, v220, v221
	v_add_f32_e32 v224, v222, v224
	v_add_f32_e32 v224, v223, v224
	ds_bpermute_b32 v225, v70, v224
	s_waitcnt lgkmcnt(0)
	v_add_f32_e32 v224, v224, v225
	ds_bpermute_b32 v225, v71, v224
	s_waitcnt lgkmcnt(0)
	v_add_f32_e32 v224, v224, v225
	ds_bpermute_b32 v225, v72, v224
	s_waitcnt lgkmcnt(0)
	v_add_f32_e32 v224, v224, v225
	ds_bpermute_b32 v225, v73, v224
	s_waitcnt lgkmcnt(0)
	v_add_f32_e32 v224, v224, v225
	ds_bpermute_b32 v225, v74, v224
	s_waitcnt lgkmcnt(0)
	v_add_f32_e32 v224, v224, v225
	ds_bpermute_b32 v225, v75, v224
	s_waitcnt lgkmcnt(0)
	v_add_f32_e32 v224, v224, v225
	v_fmamk_f32 v224, v224, 0x3a800000, v240
	v_mul_f32_e32 v225, 0x4b800000, v224
	v_cmp_gt_f32_e32 vcc, 0x800000, v224
	s_nop 1
	v_cndmask_b32_e32 v224, v224, v225, vcc
	v_rsq_f32_e32 v224, v224
	s_nop 0
	v_mul_f32_e32 v225, 0x45800000, v224
	v_cndmask_b32_e32 v226, v224, v225, vcc
	v_pk_mul_f32 v[124:125], v[124:125], v[226:227] op_sel_hi:[1,0]
	v_pk_mul_f32 v[126:127], v[126:127], v[226:227] op_sel_hi:[1,0]
	v_pk_mul_f32 v[124:125], v[76:77], v[124:125]
	v_pk_mul_f32 v[126:127], v[78:79], v[126:127]
	v_cvt_pk_bf16_f32 v228, v124, v125
	v_cvt_pk_bf16_f32 v229, v126, v127
	v_pk_mul_f32 v[128:129], v[128:129], v[226:227] op_sel_hi:[1,0]
	v_pk_mul_f32 v[130:131], v[130:131], v[226:227] op_sel_hi:[1,0]
	v_pk_mul_f32 v[128:129], v[80:81], v[128:129]
	v_pk_mul_f32 v[130:131], v[82:83], v[130:131]
	v_cvt_pk_bf16_f32 v230, v128, v129
	v_cvt_pk_bf16_f32 v231, v130, v131
	v_pk_mul_f32 v[132:133], v[132:133], v[226:227] op_sel_hi:[1,0]
	v_pk_mul_f32 v[134:135], v[134:135], v[226:227] op_sel_hi:[1,0]
	v_pk_mul_f32 v[132:133], v[84:85], v[132:133]
	v_pk_mul_f32 v[134:135], v[86:87], v[134:135]
	v_cvt_pk_bf16_f32 v232, v132, v133
	v_cvt_pk_bf16_f32 v233, v134, v135
	v_pk_mul_f32 v[136:137], v[136:137], v[226:227] op_sel_hi:[1,0]
	v_pk_mul_f32 v[138:139], v[138:139], v[226:227] op_sel_hi:[1,0]
	v_pk_mul_f32 v[136:137], v[88:89], v[136:137]
	v_pk_mul_f32 v[138:139], v[90:91], v[138:139]
	v_cvt_pk_bf16_f32 v234, v136, v137
	v_cvt_pk_bf16_f32 v235, v138, v139
	global_store_dwordx2 v69, v[228:229], s[74:75]
	global_store_dwordx2 v69, v[230:231], s[74:75] offset:512
	global_store_dwordx2 v69, v[232:233], s[74:75] offset:1024
	global_store_dwordx2 v69, v[234:235], s[74:75] offset:1536
	s_add_u32 s20, s2, 14336
	s_lshl_b32 s21, s20, 12
	s_add_u32 s24, s8, s21
	s_addc_u32 s25, s9, 0
	s_lshl_b32 s21, s20, 11
	s_add_u32 s74, s48, s21
	s_addc_u32 s75, s49, 0
	global_load_dwordx4 v[124:127], v68, s[24:25]
	global_load_dwordx4 v[128:131], v68, s[24:25] offset:1024
	global_load_dwordx4 v[132:135], v68, s[24:25] offset:2048
	global_load_dwordx4 v[136:139], v68, s[24:25] offset:3072
	s_waitcnt vmcnt(28)
; __device__ __forceinline__ u32x2 pack4(f32x4 v) { u32x2 r; r.x = cvt_pk(v[0], v[1]); r.y = cvt_pk(v[2], v[3]); return r; }
; __device__ __forceinline__ void phaseA(const Params& p, const int wv, const int rep) {
;     ...
;     auto rowsrc = [&](int r_) -> const float* {
;       const int r = r_ >= T + 2048 ? r_ - (T + 2048) : r_;
;       return r < TP ? p.in[0] + (size_t)r * 1024 : r < T ? p.in[1] + (size_t)(r - TP) * 1024 : p.in[2] + (size_t)(r - T) * 1024;
;     };
;     int r_ = gw;
;     f32x4 v[4];
;     if (r_ < rend) { const float* x = rowsrc(r_);
; #pragma unroll
;       for (int i = 0; i < 4; ++i) v[i] = *(const f32x4*)(x + (i * 64 + lane) * 4); }
;     while (r_ < rend) {
;       const int rn = r_ + nw;
;       f32x4 vn[4] = {v[0], v[1], v[2], v[3]};
;       if (rn < rend) { const float* x = rowsrc(rn);
; #pragma unroll
;         for (int i = 0; i < 4; ++i) vn[i] = *(const f32x4*)(x + (i * 64 + lane) * 4); }
;       const int r = r_ >= T + 2048 ? r_ - (T + 2048) : r_;
;       const float* w = r < T ? p.in[7] : p.in[19];
;       u16* dst = r < T ? XN + (size_t)r * 1024 : MN + (size_t)(r - T) * 1024;
;       float ss = 0.f;
; #pragma unroll
;       for (int i = 0; i < 4; ++i) ss += v[i][0] * v[i][0] + v[i][1] * v[i][1] + v[i][2] * v[i][2] + v[i][3] * v[i][3];
;       ss = wave_sum(ss);
;       const float rstd = rsqrtf(ss * (1.f / 1024.f) + EPS);
; #pragma unroll
;       for (int i = 0; i < 4; ++i) { f32x4 wv4 = *(const f32x4*)(w + (i * 64 + lane) * 4); *(u32x2*)(dst + (i * 64 + lane) * 4) = pack4(v[i] * rstd * wv4); }
; #pragma unroll
;       for (int i = 0; i < 4; ++i) v[i] = vn[i];
;       r_ = rn;
	v_pk_mul_f32 v[204:205], v[140:141], v[140:141]
	v_pk_mul_f32 v[206:207], v[142:143], v[142:143]
	v_pk_mul_f32 v[208:209], v[144:145], v[144:145]
	v_pk_mul_f32 v[210:211], v[146:147], v[146:147]
	v_pk_mul_f32 v[212:213], v[148:149], v[148:149]
	v_pk_mul_f32 v[214:215], v[150:151], v[150:151]
	v_pk_mul_f32 v[216:217], v[152:153], v[152:153]
	v_pk_mul_f32 v[218:219], v[154:155], v[154:155]
	v_add_f32_e32 v220, v204, v205
	v_add_f32_e32 v220, v206, v220
	v_add_f32_e32 v220, v207, v220
	v_add_f32_e32 v221, v208, v209
	v_add_f32_e32 v221, v210, v221
	v_add_f32_e32 v221, v211, v221
	v_add_f32_e32 v222, v212, v213
	v_add_f32_e32 v222, v214, v222
	v_add_f32_e32 v222, v215, v222
	v_add_f32_e32 v223, v216, v217
	v_add_f32_e32 v223, v218, v223
	v_add_f32_e32 v223, v219, v223
	v_add_f32_e32 v224, v220, v221
	v_add_f32_e32 v224, v222, v224
	v_add_f32_e32 v224, v223, v224
	ds_bpermute_b32 v225, v70, v224
	s_waitcnt lgkmcnt(0)
	v_add_f32_e32 v224, v224, v225
	ds_bpermute_b32 v225, v71, v224
	s_waitcnt lgkmcnt(0)
	v_add_f32_e32 v224, v224, v225
	ds_bpermute_b32 v225, v72, v224
	s_waitcnt lgkmcnt(0)
	v_add_f32_e32 v224, v224, v225
	ds_bpermute_b32 v225, v73, v224
	s_waitcnt lgkmcnt(0)
	v_add_f32_e32 v224, v224, v225
	ds_bpermute_b32 v225, v74, v224
	s_waitcnt lgkmcnt(0)
	v_add_f32_e32 v224, v224, v225
	ds_bpermute_b32 v225, v75, v224
	s_waitcnt lgkmcnt(0)
	v_add_f32_e32 v224, v224, v225
	v_fmamk_f32 v224, v224, 0x3a800000, v240
	v_mul_f32_e32 v225, 0x4b800000, v224
	v_cmp_gt_f32_e32 vcc, 0x800000, v224
	s_nop 1
	v_cndmask_b32_e32 v224, v224, v225, vcc
	v_rsq_f32_e32 v224, v224
	s_nop 0
	v_mul_f32_e32 v225, 0x45800000, v224
	v_cndmask_b32_e32 v226, v224, v225, vcc
	v_pk_mul_f32 v[140:141], v[140:141], v[226:227] op_sel_hi:[1,0]
	v_pk_mul_f32 v[142:143], v[142:143], v[226:227] op_sel_hi:[1,0]
	v_pk_mul_f32 v[140:141], v[76:77], v[140:141]
	v_pk_mul_f32 v[142:143], v[78:79], v[142:143]
	v_cvt_pk_bf16_f32 v228, v140, v141
	v_cvt_pk_bf16_f32 v229, v142, v143
	v_pk_mul_f32 v[144:145], v[144:145], v[226:227] op_sel_hi:[1,0]
	v_pk_mul_f32 v[146:147], v[146:147], v[226:227] op_sel_hi:[1,0]
	v_pk_mul_f32 v[144:145], v[80:81], v[144:145]
	v_pk_mul_f32 v[146:147], v[82:83], v[146:147]
	v_cvt_pk_bf16_f32 v230, v144, v145
	v_cvt_pk_bf16_f32 v231, v146, v147
	v_pk_mul_f32 v[148:149], v[148:149], v[226:227] op_sel_hi:[1,0]
	v_pk_mul_f32 v[150:151], v[150:151], v[226:227] op_sel_hi:[1,0]
	v_pk_mul_f32 v[148:149], v[84:85], v[148:149]
	v_pk_mul_f32 v[150:151], v[86:87], v[150:151]
	v_cvt_pk_bf16_f32 v232, v148, v149
	v_cvt_pk_bf16_f32 v233, v150, v151
	v_pk_mul_f32 v[152:153], v[152:153], v[226:227] op_sel_hi:[1,0]
	v_pk_mul_f32 v[154:155], v[154:155], v[226:227] op_sel_hi:[1,0]
	v_pk_mul_f32 v[152:153], v[88:89], v[152:153]
	v_pk_mul_f32 v[154:155], v[90:91], v[154:155]
	v_cvt_pk_bf16_f32 v234, v152, v153
	v_cvt_pk_bf16_f32 v235, v154, v155
	global_store_dwordx2 v69, v[228:229], s[76:77]
	global_store_dwordx2 v69, v[230:231], s[76:77] offset:512
	global_store_dwordx2 v69, v[232:233], s[76:77] offset:1024
	global_store_dwordx2 v69, v[234:235], s[76:77] offset:1536
	s_cmp_lt_u32 s2, 0x80
	s_cbranch_scc0 .Lrn_i8_b
	s_lshl_b32 s21, s2, 12
	s_add_u32 s24, s10, s21
	s_addc_u32 s25, s11, 0
	s_add_u32 s20, s2, 0x4000
	s_lshl_b32 s21, s20, 11
	s_add_u32 s76, s48, s21
	s_addc_u32 s77, s49, 0
	s_branch .Lrn_i8_j
.Lrn_i8_b:
	s_sub_u32 s20, s2, 128
	s_lshl_b32 s21, s20, 12
	s_add_u32 s24, s12, s21
	s_addc_u32 s25, s13, 0
	s_lshl_b32 s21, s20, 11
	s_add_u32 s76, s18, s21
	s_addc_u32 s77, s19, 0
.Lrn_i8_j:
	global_load_dwordx4 v[140:143], v68, s[24:25]
	global_load_dwordx4 v[144:147], v68, s[24:25] offset:1024
	global_load_dwordx4 v[148:151], v68, s[24:25] offset:2048
	global_load_dwordx4 v[152:155], v68, s[24:25] offset:3072
	s_waitcnt vmcnt(32)
	v_pk_mul_f32 v[204:205], v[156:157], v[156:157]
	v_pk_mul_f32 v[206:207], v[158:159], v[158:159]
	v_pk_mul_f32 v[208:209], v[160:161], v[160:161]
	v_pk_mul_f32 v[210:211], v[162:163], v[162:163]
	v_pk_mul_f32 v[212:213], v[164:165], v[164:165]
	v_pk_mul_f32 v[214:215], v[166:167], v[166:167]
	v_pk_mul_f32 v[216:217], v[168:169], v[168:169]
	v_pk_mul_f32 v[218:219], v[170:171], v[170:171]
	v_add_f32_e32 v220, v204, v205
	v_add_f32_e32 v220, v206, v220
	v_add_f32_e32 v220, v207, v220
	v_add_f32_e32 v221, v208, v209
	v_add_f32_e32 v221, v210, v221
	v_add_f32_e32 v221, v211, v221
	v_add_f32_e32 v222, v212, v213
	v_add_f32_e32 v222, v214, v222
	v_add_f32_e32 v222, v215, v222
	v_add_f32_e32 v223, v216, v217
	v_add_f32_e32 v223, v218, v223
	v_add_f32_e32 v223, v219, v223
	v_add_f32_e32 v224, v220, v221
	v_add_f32_e32 v224, v222, v224
	v_add_f32_e32 v224, v223, v224
	ds_bpermute_b32 v225, v70, v224
	s_waitcnt lgkmcnt(0)
	v_add_f32_e32 v224, v224, v225
	ds_bpermute_b32 v225, v71, v224
	s_waitcnt lgkmcnt(0)
	v_add_f32_e32 v224, v224, v225
	ds_bpermute_b32 v225, v72, v224
	s_waitcnt lgkmcnt(0)
	v_add_f32_e32 v224, v224, v225
	ds_bpermute_b32 v225, v73, v224
	s_waitcnt lgkmcnt(0)
	v_add_f32_e32 v224, v224, v225
	ds_bpermute_b32 v225, v74, v224
	s_waitcnt lgkmcnt(0)
	v_add_f32_e32 v224, v224, v225
	ds_bpermute_b32 v225, v75, v224
	s_waitcnt lgkmcnt(0)
	v_add_f32_e32 v224, v224, v225
	v_fmamk_f32 v224, v224, 0x3a800000, v240
	v_mul_f32_e32 v225, 0x4b800000, v224
	v_cmp_gt_f32_e32 vcc, 0x800000, v224
	s_nop 1
	v_cndmask_b32_e32 v224, v224, v225, vcc
	v_rsq_f32_e32 v224, v224
	s_nop 0
	v_mul_f32_e32 v225, 0x45800000, v224
	v_cndmask_b32_e32 v226, v224, v225, vcc
	v_pk_mul_f32 v[156:157], v[156:157], v[226:227] op_sel_hi:[1,0]
	v_pk_mul_f32 v[158:159], v[158:159], v[226:227] op_sel_hi:[1,0]
	v_pk_mul_f32 v[156:157], v[76:77], v[156:157]
	v_pk_mul_f32 v[158:159], v[78:79], v[158:159]
	v_cvt_pk_bf16_f32 v228, v156, v157
	v_cvt_pk_bf16_f32 v229, v158, v159
	v_pk_mul_f32 v[160:161], v[160:161], v[226:227] op_sel_hi:[1,0]
	v_pk_mul_f32 v[162:163], v[162:163], v[226:227] op_sel_hi:[1,0]
	v_pk_mul_f32 v[160:161], v[80:81], v[160:161]
	v_pk_mul_f32 v[162:163], v[82:83], v[162:163]
	v_cvt_pk_bf16_f32 v230, v160, v161
	v_cvt_pk_bf16_f32 v231, v162, v163
	v_pk_mul_f32 v[164:165], v[164:165], v[226:227] op_sel_hi:[1,0]
	v_pk_mul_f32 v[166:167], v[166:167], v[226:227] op_sel_hi:[1,0]
	v_pk_mul_f32 v[164:165], v[84:85], v[164:165]
	v_pk_mul_f32 v[166:167], v[86:87], v[166:167]
	v_cvt_pk_bf16_f32 v232, v164, v165
	v_cvt_pk_bf16_f32 v233, v166, v167
	v_pk_mul_f32 v[168:169], v[168:169], v[226:227] op_sel_hi:[1,0]
	v_pk_mul_f32 v[170:171], v[170:171], v[226:227] op_sel_hi:[1,0]
	v_pk_mul_f32 v[168:169], v[88:89], v[168:169]
	v_pk_mul_f32 v[170:171], v[90:91], v[170:171]
	v_cvt_pk_bf16_f32 v234, v168, v169
	v_cvt_pk_bf16_f32 v235, v170, v171
	global_store_dwordx2 v69, v[228:229], s[78:79]
	global_store_dwordx2 v69, v[230:231], s[78:79] offset:512
	global_store_dwordx2 v69, v[232:233], s[78:79] offset:1024
	global_store_dwordx2 v69, v[234:235], s[78:79] offset:1536
	s_cmp_lt_u32 s2, 0x80
	s_cbranch_scc0 .Lrn_no9
; __device__ __forceinline__ u32x2 pack4(f32x4 v) { u32x2 r; r.x = cvt_pk(v[0], v[1]); r.y = cvt_pk(v[2], v[3]); return r; }
; __device__ __forceinline__ void phaseA(const Params& p, const int wv, const int rep) {
;     ...
;     auto rowsrc = [&](int r_) -> const float* {
;       const int r = r_ >= T + 2048 ? r_ - (T + 2048) : r_;
;       return r < TP ? p.in[0] + (size_t)r * 1024 : r < T ? p.in[1] + (size_t)(r - TP) * 1024 : p.in[2] + (size_t)(r - T) * 1024;
;     };
;     int r_ = gw;
;     f32x4 v[4];
;     if (r_ < rend) { const float* x = rowsrc(r_);
; #pragma unroll
;       for (int i = 0; i < 4; ++i) v[i] = *(const f32x4*)(x + (i * 64 + lane) * 4); }
;     while (r_ < rend) {
;       const int rn = r_ + nw;
;       f32x4 vn[4] = {v[0], v[1], v[2], v[3]};
;       if (rn < rend) { const float* x = rowsrc(rn);
; #pragma unroll
;         for (int i = 0; i < 4; ++i) vn[i] = *(const f32x4*)(x + (i * 64 + lane) * 4); }
;       const int r = r_ >= T + 2048 ? r_ - (T + 2048) : r_;
;       const float* w = r < T ? p.in[7] : p.in[19];
;       u16* dst = r < T ? XN + (size_t)r * 1024 : MN + (size_t)(r - T) * 1024;
;       float ss = 0.f;
; #pragma unroll
;       for (int i = 0; i < 4; ++i) ss += v[i][0] * v[i][0] + v[i][1] * v[i][1] + v[i][2] * v[i][2] + v[i][3] * v[i][3];
;       ss = wave_sum(ss);
;       const float rstd = rsqrtf(ss * (1.f / 1024.f) + EPS);
; #pragma unroll
;       for (int i = 0; i < 4; ++i) { f32x4 wv4 = *(const f32x4*)(w + (i * 64 + lane) * 4); *(u32x2*)(dst + (i * 64 + lane) * 4) = pack4(v[i] * rstd * wv4); }
; #pragma unroll
;       for (int i = 0; i < 4; ++i) v[i] = vn[i];
;       r_ = rn;
	s_add_u32 s20, s2, 1920
	s_lshl_b32 s21, s20, 12
	s_add_u32 s24, s12, s21
	s_addc_u32 s25, s13, 0
	s_lshl_b32 s21, s20, 11
	s_add_u32 s78, s18, s21
	s_addc_u32 s79, s19, 0
	global_load_dwordx4 v[156:159], v68, s[24:25]
	global_load_dwordx4 v[160:163], v68, s[24:25] offset:1024
	global_load_dwordx4 v[164:167], v68, s[24:25] offset:2048
	global_load_dwordx4 v[168:171], v68, s[24:25] offset:3072
.Lrn_no9:
	s_waitcnt vmcnt(32)
	v_pk_mul_f32 v[204:205], v[172:173], v[172:173]
	v_pk_mul_f32 v[206:207], v[174:175], v[174:175]
	v_pk_mul_f32 v[208:209], v[176:177], v[176:177]
	v_pk_mul_f32 v[210:211], v[178:179], v[178:179]
	v_pk_mul_f32 v[212:213], v[180:181], v[180:181]
	v_pk_mul_f32 v[214:215], v[182:183], v[182:183]
	v_pk_mul_f32 v[216:217], v[184:185], v[184:185]
	v_pk_mul_f32 v[218:219], v[186:187], v[186:187]
	v_add_f32_e32 v220, v204, v205
	v_add_f32_e32 v220, v206, v220
	v_add_f32_e32 v220, v207, v220
	v_add_f32_e32 v221, v208, v209
	v_add_f32_e32 v221, v210, v221
	v_add_f32_e32 v221, v211, v221
	v_add_f32_e32 v222, v212, v213
	v_add_f32_e32 v222, v214, v222
	v_add_f32_e32 v222, v215, v222
	v_add_f32_e32 v223, v216, v217
	v_add_f32_e32 v223, v218, v223
	v_add_f32_e32 v223, v219, v223
	v_add_f32_e32 v224, v220, v221
	v_add_f32_e32 v224, v222, v224
	v_add_f32_e32 v224, v223, v224
	ds_bpermute_b32 v225, v70, v224
	s_waitcnt lgkmcnt(0)
	v_add_f32_e32 v224, v224, v225
	ds_bpermute_b32 v225, v71, v224
	s_waitcnt lgkmcnt(0)
	v_add_f32_e32 v224, v224, v225
	ds_bpermute_b32 v225, v72, v224
	s_waitcnt lgkmcnt(0)
	v_add_f32_e32 v224, v224, v225
	ds_bpermute_b32 v225, v73, v224
	s_waitcnt lgkmcnt(0)
	v_add_f32_e32 v224, v224, v225
	ds_bpermute_b32 v225, v74, v224
	s_waitcnt lgkmcnt(0)
	v_add_f32_e32 v224, v224, v225
	ds_bpermute_b32 v225, v75, v224
	s_waitcnt lgkmcnt(0)
	v_add_f32_e32 v224, v224, v225
	v_fmamk_f32 v224, v224, 0x3a800000, v240
	v_mul_f32_e32 v225, 0x4b800000, v224
	v_cmp_gt_f32_e32 vcc, 0x800000, v224
	s_nop 1
	v_cndmask_b32_e32 v224, v224, v225, vcc
	v_rsq_f32_e32 v224, v224
	s_nop 0
	v_mul_f32_e32 v225, 0x45800000, v224
	v_cndmask_b32_e32 v226, v224, v225, vcc
	v_pk_mul_f32 v[172:173], v[172:173], v[226:227] op_sel_hi:[1,0]
	v_pk_mul_f32 v[174:175], v[174:175], v[226:227] op_sel_hi:[1,0]
	v_pk_mul_f32 v[172:173], v[76:77], v[172:173]
	v_pk_mul_f32 v[174:175], v[78:79], v[174:175]
	v_cvt_pk_bf16_f32 v228, v172, v173
	v_cvt_pk_bf16_f32 v229, v174, v175
	v_pk_mul_f32 v[176:177], v[176:177], v[226:227] op_sel_hi:[1,0]
	v_pk_mul_f32 v[178:179], v[178:179], v[226:227] op_sel_hi:[1,0]
	v_pk_mul_f32 v[176:177], v[80:81], v[176:177]
	v_pk_mul_f32 v[178:179], v[82:83], v[178:179]
	v_cvt_pk_bf16_f32 v230, v176, v177
	v_cvt_pk_bf16_f32 v231, v178, v179
	v_pk_mul_f32 v[180:181], v[180:181], v[226:227] op_sel_hi:[1,0]
	v_pk_mul_f32 v[182:183], v[182:183], v[226:227] op_sel_hi:[1,0]
	v_pk_mul_f32 v[180:181], v[84:85], v[180:181]
	v_pk_mul_f32 v[182:183], v[86:87], v[182:183]
	v_cvt_pk_bf16_f32 v232, v180, v181
	v_cvt_pk_bf16_f32 v233, v182, v183
	v_pk_mul_f32 v[184:185], v[184:185], v[226:227] op_sel_hi:[1,0]
	v_pk_mul_f32 v[186:187], v[186:187], v[226:227] op_sel_hi:[1,0]
	v_pk_mul_f32 v[184:185], v[88:89], v[184:185]
	v_pk_mul_f32 v[186:187], v[90:91], v[186:187]
	v_cvt_pk_bf16_f32 v234, v184, v185
	v_cvt_pk_bf16_f32 v235, v186, v187
	global_store_dwordx2 v69, v[228:229], s[84:85]
	global_store_dwordx2 v69, v[230:231], s[84:85] offset:512
	global_store_dwordx2 v69, v[232:233], s[84:85] offset:1024
	global_store_dwordx2 v69, v[234:235], s[84:85] offset:1536
	s_waitcnt vmcnt(32)
	v_pk_mul_f32 v[204:205], v[188:189], v[188:189]
	v_pk_mul_f32 v[206:207], v[190:191], v[190:191]
	v_pk_mul_f32 v[208:209], v[192:193], v[192:193]
	v_pk_mul_f32 v[210:211], v[194:195], v[194:195]
	v_pk_mul_f32 v[212:213], v[196:197], v[196:197]
	v_pk_mul_f32 v[214:215], v[198:199], v[198:199]
	v_pk_mul_f32 v[216:217], v[200:201], v[200:201]
	v_pk_mul_f32 v[218:219], v[202:203], v[202:203]
	v_add_f32_e32 v220, v204, v205
	v_add_f32_e32 v220, v206, v220
	v_add_f32_e32 v220, v207, v220
	v_add_f32_e32 v221, v208, v209
	v_add_f32_e32 v221, v210, v221
	v_add_f32_e32 v221, v211, v221
	v_add_f32_e32 v222, v212, v213
	v_add_f32_e32 v222, v214, v222
	v_add_f32_e32 v222, v215, v222
	v_add_f32_e32 v223, v216, v217
	v_add_f32_e32 v223, v218, v223
	v_add_f32_e32 v223, v219, v223
	v_add_f32_e32 v224, v220, v221
	v_add_f32_e32 v224, v222, v224
	v_add_f32_e32 v224, v223, v224
	ds_bpermute_b32 v225, v70, v224
	s_waitcnt lgkmcnt(0)
	v_add_f32_e32 v224, v224, v225
	ds_bpermute_b32 v225, v71, v224
	s_waitcnt lgkmcnt(0)
	v_add_f32_e32 v224, v224, v225
	ds_bpermute_b32 v225, v72, v224
	s_waitcnt lgkmcnt(0)
	v_add_f32_e32 v224, v224, v225
	ds_bpermute_b32 v225, v73, v224
	s_waitcnt lgkmcnt(0)
	v_add_f32_e32 v224, v224, v225
	ds_bpermute_b32 v225, v74, v224
	s_waitcnt lgkmcnt(0)
	v_add_f32_e32 v224, v224, v225
	ds_bpermute_b32 v225, v75, v224
	s_waitcnt lgkmcnt(0)
; __device__ __forceinline__ u32x2 pack4(f32x4 v) { u32x2 r; r.x = cvt_pk(v[0], v[1]); r.y = cvt_pk(v[2], v[3]); return r; }
; __device__ __forceinline__ void phaseA(const Params& p, const int wv, const int rep) {
;     ...
;       float ss = 0.f;
; #pragma unroll
;       for (int i = 0; i < 4; ++i) ss += v[i][0] * v[i][0] + v[i][1] * v[i][1] + v[i][2] * v[i][2] + v[i][3] * v[i][3];
;       ss = wave_sum(ss);
;       const float rstd = rsqrtf(ss * (1.f / 1024.f) + EPS);
; #pragma unroll
;       for (int i = 0; i < 4; ++i) { f32x4 wv4 = *(const f32x4*)(w + (i * 64 + lane) * 4); *(u32x2*)(dst + (i * 64 + lane) * 4) = pack4(v[i] * rstd * wv4); }
; #pragma unroll
;       for (int i = 0; i < 4; ++i) v[i] = vn[i];
;       r_ = rn;
	v_add_f32_e32 v224, v224, v225
	v_fmamk_f32 v224, v224, 0x3a800000, v240
	v_mul_f32_e32 v225, 0x4b800000, v224
	v_cmp_gt_f32_e32 vcc, 0x800000, v224
	s_nop 1
	v_cndmask_b32_e32 v224, v224, v225, vcc
	v_rsq_f32_e32 v224, v224
	s_nop 0
	v_mul_f32_e32 v225, 0x45800000, v224
	v_cndmask_b32_e32 v226, v224, v225, vcc
	v_pk_mul_f32 v[188:189], v[188:189], v[226:227] op_sel_hi:[1,0]
	v_pk_mul_f32 v[190:191], v[190:191], v[226:227] op_sel_hi:[1,0]
	v_pk_mul_f32 v[188:189], v[76:77], v[188:189]
	v_pk_mul_f32 v[190:191], v[78:79], v[190:191]
	v_cvt_pk_bf16_f32 v228, v188, v189
	v_cvt_pk_bf16_f32 v229, v190, v191
	v_pk_mul_f32 v[192:193], v[192:193], v[226:227] op_sel_hi:[1,0]
	v_pk_mul_f32 v[194:195], v[194:195], v[226:227] op_sel_hi:[1,0]
	v_pk_mul_f32 v[192:193], v[80:81], v[192:193]
	v_pk_mul_f32 v[194:195], v[82:83], v[194:195]
	v_cvt_pk_bf16_f32 v230, v192, v193
	v_cvt_pk_bf16_f32 v231, v194, v195
	v_pk_mul_f32 v[196:197], v[196:197], v[226:227] op_sel_hi:[1,0]
	v_pk_mul_f32 v[198:199], v[198:199], v[226:227] op_sel_hi:[1,0]
	v_pk_mul_f32 v[196:197], v[84:85], v[196:197]
	v_pk_mul_f32 v[198:199], v[86:87], v[198:199]
	v_cvt_pk_bf16_f32 v232, v196, v197
	v_cvt_pk_bf16_f32 v233, v198, v199
	v_pk_mul_f32 v[200:201], v[200:201], v[226:227] op_sel_hi:[1,0]
	v_pk_mul_f32 v[202:203], v[202:203], v[226:227] op_sel_hi:[1,0]
	v_pk_mul_f32 v[200:201], v[88:89], v[200:201]
	v_pk_mul_f32 v[202:203], v[90:91], v[202:203]
	v_cvt_pk_bf16_f32 v234, v200, v201
	v_cvt_pk_bf16_f32 v235, v202, v203
	global_store_dwordx2 v69, v[228:229], s[86:87]
	global_store_dwordx2 v69, v[230:231], s[86:87] offset:512
	global_store_dwordx2 v69, v[232:233], s[86:87] offset:1024
	global_store_dwordx2 v69, v[234:235], s[86:87] offset:1536
	s_waitcnt vmcnt(28)
	v_pk_mul_f32 v[204:205], v[108:109], v[108:109]
	v_pk_mul_f32 v[206:207], v[110:111], v[110:111]
	v_pk_mul_f32 v[208:209], v[112:113], v[112:113]
	v_pk_mul_f32 v[210:211], v[114:115], v[114:115]
	v_pk_mul_f32 v[212:213], v[116:117], v[116:117]
	v_pk_mul_f32 v[214:215], v[118:119], v[118:119]
	v_pk_mul_f32 v[216:217], v[120:121], v[120:121]
	v_pk_mul_f32 v[218:219], v[122:123], v[122:123]
	v_add_f32_e32 v220, v204, v205
	v_add_f32_e32 v220, v206, v220
	v_add_f32_e32 v220, v207, v220
	v_add_f32_e32 v221, v208, v209
	v_add_f32_e32 v221, v210, v221
	v_add_f32_e32 v221, v211, v221
	v_add_f32_e32 v222, v212, v213
	v_add_f32_e32 v222, v214, v222
	v_add_f32_e32 v222, v215, v222
	v_add_f32_e32 v223, v216, v217
	v_add_f32_e32 v223, v218, v223
	v_add_f32_e32 v223, v219, v223
	v_add_f32_e32 v224, v220, v221
	v_add_f32_e32 v224, v222, v224
	v_add_f32_e32 v224, v223, v224
	ds_bpermute_b32 v225, v70, v224
	s_waitcnt lgkmcnt(0)
	v_add_f32_e32 v224, v224, v225
	ds_bpermute_b32 v225, v71, v224
	s_waitcnt lgkmcnt(0)
	v_add_f32_e32 v224, v224, v225
	ds_bpermute_b32 v225, v72, v224
	s_waitcnt lgkmcnt(0)
	v_add_f32_e32 v224, v224, v225
	ds_bpermute_b32 v225, v73, v224
	s_waitcnt lgkmcnt(0)
	v_add_f32_e32 v224, v224, v225
	ds_bpermute_b32 v225, v74, v224
	s_waitcnt lgkmcnt(0)
	v_add_f32_e32 v224, v224, v225
	ds_bpermute_b32 v225, v75, v224
	s_waitcnt lgkmcnt(0)
	v_add_f32_e32 v224, v224, v225
	v_fmamk_f32 v224, v224, 0x3a800000, v240
	v_mul_f32_e32 v225, 0x4b800000, v224
	v_cmp_gt_f32_e32 vcc, 0x800000, v224
	s_nop 1
	v_cndmask_b32_e32 v224, v224, v225, vcc
	v_rsq_f32_e32 v224, v224
	s_nop 0
	v_mul_f32_e32 v225, 0x45800000, v224
	v_cndmask_b32_e32 v226, v224, v225, vcc
	v_pk_mul_f32 v[108:109], v[108:109], v[226:227] op_sel_hi:[1,0]
	v_pk_mul_f32 v[110:111], v[110:111], v[226:227] op_sel_hi:[1,0]
	v_pk_mul_f32 v[108:109], v[76:77], v[108:109]
	v_pk_mul_f32 v[110:111], v[78:79], v[110:111]
	v_cvt_pk_bf16_f32 v228, v108, v109
	v_cvt_pk_bf16_f32 v229, v110, v111
	v_pk_mul_f32 v[112:113], v[112:113], v[226:227] op_sel_hi:[1,0]
	v_pk_mul_f32 v[114:115], v[114:115], v[226:227] op_sel_hi:[1,0]
	v_pk_mul_f32 v[112:113], v[80:81], v[112:113]
	v_pk_mul_f32 v[114:115], v[82:83], v[114:115]
	v_cvt_pk_bf16_f32 v230, v112, v113
	v_cvt_pk_bf16_f32 v231, v114, v115
	v_pk_mul_f32 v[116:117], v[116:117], v[226:227] op_sel_hi:[1,0]
	v_pk_mul_f32 v[118:119], v[118:119], v[226:227] op_sel_hi:[1,0]
	v_pk_mul_f32 v[116:117], v[84:85], v[116:117]
	v_pk_mul_f32 v[118:119], v[86:87], v[118:119]
	v_cvt_pk_bf16_f32 v232, v116, v117
	v_cvt_pk_bf16_f32 v233, v118, v119
	v_pk_mul_f32 v[120:121], v[120:121], v[226:227] op_sel_hi:[1,0]
	v_pk_mul_f32 v[122:123], v[122:123], v[226:227] op_sel_hi:[1,0]
	v_pk_mul_f32 v[120:121], v[88:89], v[120:121]
	v_pk_mul_f32 v[122:123], v[90:91], v[122:123]
	v_cvt_pk_bf16_f32 v234, v120, v121
	v_cvt_pk_bf16_f32 v235, v122, v123
	global_store_dwordx2 v69, v[228:229], s[72:73]
	global_store_dwordx2 v69, v[230:231], s[72:73] offset:512
	global_store_dwordx2 v69, v[232:233], s[72:73] offset:1024
	global_store_dwordx2 v69, v[234:235], s[72:73] offset:1536
	s_waitcnt vmcnt(24)
	v_pk_mul_f32 v[204:205], v[124:125], v[124:125]
	v_pk_mul_f32 v[206:207], v[126:127], v[126:127]
	v_pk_mul_f32 v[208:209], v[128:129], v[128:129]
	v_pk_mul_f32 v[210:211], v[130:131], v[130:131]
	v_pk_mul_f32 v[212:213], v[132:133], v[132:133]
	v_pk_mul_f32 v[214:215], v[134:135], v[134:135]
	v_pk_mul_f32 v[216:217], v[136:137], v[136:137]
	v_pk_mul_f32 v[218:219], v[138:139], v[138:139]
	v_add_f32_e32 v220, v204, v205
	v_add_f32_e32 v220, v206, v220
	v_add_f32_e32 v220, v207, v220
	v_add_f32_e32 v221, v208, v209
	v_add_f32_e32 v221, v210, v221
	v_add_f32_e32 v221, v211, v221
	v_add_f32_e32 v222, v212, v213
	v_add_f32_e32 v222, v214, v222
	v_add_f32_e32 v222, v215, v222
	v_add_f32_e32 v223, v216, v217
	v_add_f32_e32 v223, v218, v223
	v_add_f32_e32 v223, v219, v223
	v_add_f32_e32 v224, v220, v221
	v_add_f32_e32 v224, v222, v224
	v_add_f32_e32 v224, v223, v224
	ds_bpermute_b32 v225, v70, v224
	s_waitcnt lgkmcnt(0)
; __device__ __forceinline__ u32x2 pack4(f32x4 v) { u32x2 r; r.x = cvt_pk(v[0], v[1]); r.y = cvt_pk(v[2], v[3]); return r; }
; __device__ __forceinline__ void phaseA(const Params& p, const int wv, const int rep) {
;     ...
;       const int r = r_ >= T + 2048 ? r_ - (T + 2048) : r_;
;       const float* w = r < T ? p.in[7] : p.in[19];
;       u16* dst = r < T ? XN + (size_t)r * 1024 : MN + (size_t)(r - T) * 1024;
;       float ss = 0.f;
; #pragma unroll
;       for (int i = 0; i < 4; ++i) ss += v[i][0] * v[i][0] + v[i][1] * v[i][1] + v[i][2] * v[i][2] + v[i][3] * v[i][3];
;       ss = wave_sum(ss);
;       const float rstd = rsqrtf(ss * (1.f / 1024.f) + EPS);
; #pragma unroll
;       for (int i = 0; i < 4; ++i) { f32x4 wv4 = *(const f32x4*)(w + (i * 64 + lane) * 4); *(u32x2*)(dst + (i * 64 + lane) * 4) = pack4(v[i] * rstd * wv4); }
	v_add_f32_e32 v224, v224, v225
	ds_bpermute_b32 v225, v71, v224
	s_waitcnt lgkmcnt(0)
	v_add_f32_e32 v224, v224, v225
	ds_bpermute_b32 v225, v72, v224
	s_waitcnt lgkmcnt(0)
	v_add_f32_e32 v224, v224, v225
	ds_bpermute_b32 v225, v73, v224
	s_waitcnt lgkmcnt(0)
	v_add_f32_e32 v224, v224, v225
	ds_bpermute_b32 v225, v74, v224
	s_waitcnt lgkmcnt(0)
	v_add_f32_e32 v224, v224, v225
	ds_bpermute_b32 v225, v75, v224
	s_waitcnt lgkmcnt(0)
	v_add_f32_e32 v224, v224, v225
	v_fmamk_f32 v224, v224, 0x3a800000, v240
	v_mul_f32_e32 v225, 0x4b800000, v224
	v_cmp_gt_f32_e32 vcc, 0x800000, v224
	s_nop 1
	v_cndmask_b32_e32 v224, v224, v225, vcc
	v_rsq_f32_e32 v224, v224
	s_nop 0
	v_mul_f32_e32 v225, 0x45800000, v224
	v_cndmask_b32_e32 v226, v224, v225, vcc
	v_pk_mul_f32 v[124:125], v[124:125], v[226:227] op_sel_hi:[1,0]
	v_pk_mul_f32 v[126:127], v[126:127], v[226:227] op_sel_hi:[1,0]
	v_pk_mul_f32 v[124:125], v[76:77], v[124:125]
	v_pk_mul_f32 v[126:127], v[78:79], v[126:127]
	v_cvt_pk_bf16_f32 v228, v124, v125
	v_cvt_pk_bf16_f32 v229, v126, v127
	v_pk_mul_f32 v[128:129], v[128:129], v[226:227] op_sel_hi:[1,0]
	v_pk_mul_f32 v[130:131], v[130:131], v[226:227] op_sel_hi:[1,0]
	v_pk_mul_f32 v[128:129], v[80:81], v[128:129]
	v_pk_mul_f32 v[130:131], v[82:83], v[130:131]
	v_cvt_pk_bf16_f32 v230, v128, v129
	v_cvt_pk_bf16_f32 v231, v130, v131
	v_pk_mul_f32 v[132:133], v[132:133], v[226:227] op_sel_hi:[1,0]
	v_pk_mul_f32 v[134:135], v[134:135], v[226:227] op_sel_hi:[1,0]
	v_pk_mul_f32 v[132:133], v[84:85], v[132:133]
	v_pk_mul_f32 v[134:135], v[86:87], v[134:135]
	v_cvt_pk_bf16_f32 v232, v132, v133
	v_cvt_pk_bf16_f32 v233, v134, v135
	v_pk_mul_f32 v[136:137], v[136:137], v[226:227] op_sel_hi:[1,0]
	v_pk_mul_f32 v[138:139], v[138:139], v[226:227] op_sel_hi:[1,0]
	v_pk_mul_f32 v[136:137], v[88:89], v[136:137]
	v_pk_mul_f32 v[138:139], v[90:91], v[138:139]
	v_cvt_pk_bf16_f32 v234, v136, v137
	v_cvt_pk_bf16_f32 v235, v138, v139
	global_store_dwordx2 v69, v[228:229], s[74:75]
	global_store_dwordx2 v69, v[230:231], s[74:75] offset:512
	global_store_dwordx2 v69, v[232:233], s[74:75] offset:1024
	global_store_dwordx2 v69, v[234:235], s[74:75] offset:1536
	s_waitcnt vmcnt(20)
	v_pk_mul_f32 v[204:205], v[140:141], v[140:141]
	v_pk_mul_f32 v[206:207], v[142:143], v[142:143]
	v_pk_mul_f32 v[208:209], v[144:145], v[144:145]
	v_pk_mul_f32 v[210:211], v[146:147], v[146:147]
	v_pk_mul_f32 v[212:213], v[148:149], v[148:149]
	v_pk_mul_f32 v[214:215], v[150:151], v[150:151]
	v_pk_mul_f32 v[216:217], v[152:153], v[152:153]
	v_pk_mul_f32 v[218:219], v[154:155], v[154:155]
	v_add_f32_e32 v220, v204, v205
	v_add_f32_e32 v220, v206, v220
	v_add_f32_e32 v220, v207, v220
	v_add_f32_e32 v221, v208, v209
	v_add_f32_e32 v221, v210, v221
	v_add_f32_e32 v221, v211, v221
	v_add_f32_e32 v222, v212, v213
	v_add_f32_e32 v222, v214, v222
	v_add_f32_e32 v222, v215, v222
	v_add_f32_e32 v223, v216, v217
	v_add_f32_e32 v223, v218, v223
	v_add_f32_e32 v223, v219, v223
	v_add_f32_e32 v224, v220, v221
	v_add_f32_e32 v224, v222, v224
	v_add_f32_e32 v224, v223, v224
	ds_bpermute_b32 v225, v70, v224
	s_waitcnt lgkmcnt(0)
	v_add_f32_e32 v224, v224, v225
	ds_bpermute_b32 v225, v71, v224
	s_waitcnt lgkmcnt(0)
	v_add_f32_e32 v224, v224, v225
	ds_bpermute_b32 v225, v72, v224
	s_waitcnt lgkmcnt(0)
	v_add_f32_e32 v224, v224, v225
	ds_bpermute_b32 v225, v73, v224
	s_waitcnt lgkmcnt(0)
	v_add_f32_e32 v224, v224, v225
	ds_bpermute_b32 v225, v74, v224
	s_waitcnt lgkmcnt(0)
	v_add_f32_e32 v224, v224, v225
	ds_bpermute_b32 v225, v75, v224
	s_waitcnt lgkmcnt(0)
	v_add_f32_e32 v224, v224, v225
	v_fmamk_f32 v224, v224, 0x3a800000, v240
	v_mul_f32_e32 v225, 0x4b800000, v224
	v_cmp_gt_f32_e32 vcc, 0x800000, v224
	s_nop 1
	v_cndmask_b32_e32 v224, v224, v225, vcc
	v_rsq_f32_e32 v224, v224
	s_nop 0
	v_mul_f32_e32 v225, 0x45800000, v224
	v_cndmask_b32_e32 v226, v224, v225, vcc
	s_cmp_lt_u32 s2, 0x80
	s_cbranch_scc0 .Lrn_p8_b
	v_pk_mul_f32 v[140:141], v[140:141], v[226:227] op_sel_hi:[1,0]
	v_pk_mul_f32 v[142:143], v[142:143], v[226:227] op_sel_hi:[1,0]
	v_pk_mul_f32 v[140:141], v[76:77], v[140:141]
	v_pk_mul_f32 v[142:143], v[78:79], v[142:143]
	v_cvt_pk_bf16_f32 v228, v140, v141
	v_cvt_pk_bf16_f32 v229, v142, v143
	v_pk_mul_f32 v[144:145], v[144:145], v[226:227] op_sel_hi:[1,0]
	v_pk_mul_f32 v[146:147], v[146:147], v[226:227] op_sel_hi:[1,0]
	v_pk_mul_f32 v[144:145], v[80:81], v[144:145]
	v_pk_mul_f32 v[146:147], v[82:83], v[146:147]
	v_cvt_pk_bf16_f32 v230, v144, v145
	v_cvt_pk_bf16_f32 v231, v146, v147
	v_pk_mul_f32 v[148:149], v[148:149], v[226:227] op_sel_hi:[1,0]
	v_pk_mul_f32 v[150:151], v[150:151], v[226:227] op_sel_hi:[1,0]
	v_pk_mul_f32 v[148:149], v[84:85], v[148:149]
	v_pk_mul_f32 v[150:151], v[86:87], v[150:151]
	v_cvt_pk_bf16_f32 v232, v148, v149
	v_cvt_pk_bf16_f32 v233, v150, v151
	v_pk_mul_f32 v[152:153], v[152:153], v[226:227] op_sel_hi:[1,0]
	v_pk_mul_f32 v[154:155], v[154:155], v[226:227] op_sel_hi:[1,0]
	v_pk_mul_f32 v[152:153], v[88:89], v[152:153]
	v_pk_mul_f32 v[154:155], v[90:91], v[154:155]
	v_cvt_pk_bf16_f32 v234, v152, v153
	v_cvt_pk_bf16_f32 v235, v154, v155
	s_branch .Lrn_p8_j
; __device__ __forceinline__ u32x2 pack4(f32x4 v) { u32x2 r; r.x = cvt_pk(v[0], v[1]); r.y = cvt_pk(v[2], v[3]); return r; }
; __device__ __forceinline__ void phaseA(const Params& p, const int wv, const int rep) {
;     ...
;       const int r = r_ >= T + 2048 ? r_ - (T + 2048) : r_;
;       const float* w = r < T ? p.in[7] : p.in[19];
;       u16* dst = r < T ? XN + (size_t)r * 1024 : MN + (size_t)(r - T) * 1024;
;       float ss = 0.f;
; #pragma unroll
;       for (int i = 0; i < 4; ++i) ss += v[i][0] * v[i][0] + v[i][1] * v[i][1] + v[i][2] * v[i][2] + v[i][3] * v[i][3];
;       ss = wave_sum(ss);
;       const float rstd = rsqrtf(ss * (1.f / 1024.f) + EPS);
; #pragma unroll
;       for (int i = 0; i < 4; ++i) { f32x4 wv4 = *(const f32x4*)(w + (i * 64 + lane) * 4); *(u32x2*)(dst + (i * 64 + lane) * 4) = pack4(v[i] * rstd * wv4); }
.Lrn_p8_b:
	v_pk_mul_f32 v[140:141], v[140:141], v[226:227] op_sel_hi:[1,0]
	v_pk_mul_f32 v[142:143], v[142:143], v[226:227] op_sel_hi:[1,0]
	v_pk_mul_f32 v[140:141], v[92:93], v[140:141]
	v_pk_mul_f32 v[142:143], v[94:95], v[142:143]
	v_cvt_pk_bf16_f32 v228, v140, v141
	v_cvt_pk_bf16_f32 v229, v142, v143
	v_pk_mul_f32 v[144:145], v[144:145], v[226:227] op_sel_hi:[1,0]
	v_pk_mul_f32 v[146:147], v[146:147], v[226:227] op_sel_hi:[1,0]
	v_pk_mul_f32 v[144:145], v[96:97], v[144:145]
	v_pk_mul_f32 v[146:147], v[98:99], v[146:147]
	v_cvt_pk_bf16_f32 v230, v144, v145
	v_cvt_pk_bf16_f32 v231, v146, v147
	v_pk_mul_f32 v[148:149], v[148:149], v[226:227] op_sel_hi:[1,0]
	v_pk_mul_f32 v[150:151], v[150:151], v[226:227] op_sel_hi:[1,0]
	v_pk_mul_f32 v[148:149], v[100:101], v[148:149]
	v_pk_mul_f32 v[150:151], v[102:103], v[150:151]
	v_cvt_pk_bf16_f32 v232, v148, v149
	v_cvt_pk_bf16_f32 v233, v150, v151
	v_pk_mul_f32 v[152:153], v[152:153], v[226:227] op_sel_hi:[1,0]
	v_pk_mul_f32 v[154:155], v[154:155], v[226:227] op_sel_hi:[1,0]
	v_pk_mul_f32 v[152:153], v[104:105], v[152:153]
	v_pk_mul_f32 v[154:155], v[106:107], v[154:155]
	v_cvt_pk_bf16_f32 v234, v152, v153
	v_cvt_pk_bf16_f32 v235, v154, v155
.Lrn_p8_j:
	global_store_dwordx2 v69, v[228:229], s[76:77]
	global_store_dwordx2 v69, v[230:231], s[76:77] offset:512
	global_store_dwordx2 v69, v[232:233], s[76:77] offset:1024
	global_store_dwordx2 v69, v[234:235], s[76:77] offset:1536
	s_cmp_lt_u32 s2, 0x80
	s_cbranch_scc0 .Lrn_done
	s_waitcnt vmcnt(20)
	v_pk_mul_f32 v[204:205], v[156:157], v[156:157]
	v_pk_mul_f32 v[206:207], v[158:159], v[158:159]
	v_pk_mul_f32 v[208:209], v[160:161], v[160:161]
	v_pk_mul_f32 v[210:211], v[162:163], v[162:163]
	v_pk_mul_f32 v[212:213], v[164:165], v[164:165]
	v_pk_mul_f32 v[214:215], v[166:167], v[166:167]
	v_pk_mul_f32 v[216:217], v[168:169], v[168:169]
	v_pk_mul_f32 v[218:219], v[170:171], v[170:171]
	v_add_f32_e32 v220, v204, v205
	v_add_f32_e32 v220, v206, v220
	v_add_f32_e32 v220, v207, v220
	v_add_f32_e32 v221, v208, v209
	v_add_f32_e32 v221, v210, v221
	v_add_f32_e32 v221, v211, v221
	v_add_f32_e32 v222, v212, v213
	v_add_f32_e32 v222, v214, v222
	v_add_f32_e32 v222, v215, v222
	v_add_f32_e32 v223, v216, v217
	v_add_f32_e32 v223, v218, v223
	v_add_f32_e32 v223, v219, v223
	v_add_f32_e32 v224, v220, v221
	v_add_f32_e32 v224, v222, v224
	v_add_f32_e32 v224, v223, v224
	ds_bpermute_b32 v225, v70, v224
	s_waitcnt lgkmcnt(0)
	v_add_f32_e32 v224, v224, v225
	ds_bpermute_b32 v225, v71, v224
	s_waitcnt lgkmcnt(0)
	v_add_f32_e32 v224, v224, v225
	ds_bpermute_b32 v225, v72, v224
	s_waitcnt lgkmcnt(0)
	v_add_f32_e32 v224, v224, v225
	ds_bpermute_b32 v225, v73, v224
	s_waitcnt lgkmcnt(0)
	v_add_f32_e32 v224, v224, v225
	ds_bpermute_b32 v225, v74, v224
	s_waitcnt lgkmcnt(0)
	v_add_f32_e32 v224, v224, v225
	ds_bpermute_b32 v225, v75, v224
	s_waitcnt lgkmcnt(0)
	v_add_f32_e32 v224, v224, v225
	v_fmamk_f32 v224, v224, 0x3a800000, v240
	v_mul_f32_e32 v225, 0x4b800000, v224
	v_cmp_gt_f32_e32 vcc, 0x800000, v224
	s_nop 1
	v_cndmask_b32_e32 v224, v224, v225, vcc
	v_rsq_f32_e32 v224, v224
	s_nop 0
	v_mul_f32_e32 v225, 0x45800000, v224
	v_cndmask_b32_e32 v226, v224, v225, vcc
	v_pk_mul_f32 v[156:157], v[156:157], v[226:227] op_sel_hi:[1,0]
	v_pk_mul_f32 v[158:159], v[158:159], v[226:227] op_sel_hi:[1,0]
	v_pk_mul_f32 v[156:157], v[92:93], v[156:157]
	v_pk_mul_f32 v[158:159], v[94:95], v[158:159]
	v_cvt_pk_bf16_f32 v228, v156, v157
	v_cvt_pk_bf16_f32 v229, v158, v159
	v_pk_mul_f32 v[160:161], v[160:161], v[226:227] op_sel_hi:[1,0]
	v_pk_mul_f32 v[162:163], v[162:163], v[226:227] op_sel_hi:[1,0]
	v_pk_mul_f32 v[160:161], v[96:97], v[160:161]
	v_pk_mul_f32 v[162:163], v[98:99], v[162:163]
	v_cvt_pk_bf16_f32 v230, v160, v161
	v_cvt_pk_bf16_f32 v231, v162, v163
	v_pk_mul_f32 v[164:165], v[164:165], v[226:227] op_sel_hi:[1,0]
	v_pk_mul_f32 v[166:167], v[166:167], v[226:227] op_sel_hi:[1,0]
	v_pk_mul_f32 v[164:165], v[100:101], v[164:165]
	v_pk_mul_f32 v[166:167], v[102:103], v[166:167]
	v_cvt_pk_bf16_f32 v232, v164, v165
	v_cvt_pk_bf16_f32 v233, v166, v167
	v_pk_mul_f32 v[168:169], v[168:169], v[226:227] op_sel_hi:[1,0]
	v_pk_mul_f32 v[170:171], v[170:171], v[226:227] op_sel_hi:[1,0]
	v_pk_mul_f32 v[168:169], v[104:105], v[168:169]
	v_pk_mul_f32 v[170:171], v[106:107], v[170:171]
	v_cvt_pk_bf16_f32 v234, v168, v169
	v_cvt_pk_bf16_f32 v235, v170, v171
	global_store_dwordx2 v69, v[228:229], s[78:79]
	global_store_dwordx2 v69, v[230:231], s[78:79] offset:512
	global_store_dwordx2 v69, v[232:233], s[78:79] offset:1024
	global_store_dwordx2 v69, v[234:235], s[78:79] offset:1536

; __device__ __forceinline__ void phaseA(const Params& p, const int wv, const int rep) {
;     ...
;     const int rend = (T + 2048) * rep;
;     auto rowsrc = [&](int r_) -> const float* {
;       const int r = r_ >= T + 2048 ? r_ - (T + 2048) : r_;
;       return r < TP ? p.in[0] + (size_t)r * 1024 : r < T ? p.in[1] + (size_t)(r - TP) * 1024 : p.in[2] + (size_t)(r - T) * 1024;
;     };
;     int r_ = gw;
;     f32x4 v[4];
;     if (r_ < rend) { const float* x = rowsrc(r_);
; #pragma unroll
;       for (int i = 0; i < 4; ++i) v[i] = *(const f32x4*)(x + (i * 64 + lane) * 4); }
;     while (r_ < rend) {
;       const int rn = r_ + nw;
;       f32x4 vn[4] = {v[0], v[1], v[2], v[3]};
;       if (rn < rend) { const float* x = rowsrc(rn);
; #pragma unroll
;         for (int i = 0; i < 4; ++i) vn[i] = *(const f32x4*)(x + (i * 64 + lane) * 4); }
;       const int r = r_ >= T + 2048 ? r_ - (T + 2048) : r_;
;       const float* w = r < T ? p.in[7] : p.in[19];
;       u16* dst = r < T ? XN + (size_t)r * 1024 : MN + (size_t)(r - T) * 1024;
.Lrn_skip:
	s_mulk_i32 s33, 0x4880
	s_mov_b32 s0, s2
	v_writelane_b32 v251, s0, 56
	s_cmp_ge_i32 s2, s33
	s_nop 0
	v_writelane_b32 v251, s1, 57
	s_cbranch_scc1 .LBB0_110
	v_readlane_b32 s0, v251, 56
	s_mov_b32 s2, s0
	s_addk_i32 s0, 0xb780
	s_cmpk_gt_i32 s2, 0x487f
	s_cselect_b32 s0, s0, s2
	s_cmpk_gt_i32 s0, 0x3fff
	v_readlane_b32 s1, v251, 57
	s_cbranch_scc0 .LBB0_92
	s_cmpk_gt_u32 s0, 0x407f
	s_cbranch_scc0 .LBB0_93
	v_readlane_b32 s56, v251, 6
	v_readlane_b32 s60, v251, 10
	v_readlane_b32 s61, v251, 11
	s_add_i32 s8, s0, 0xffffbf80
	s_mov_b32 s9, 0
	v_readlane_b32 s57, v251, 7
	v_readlane_b32 s58, v251, 8
	v_readlane_b32 s59, v251, 9
	v_readlane_b32 s62, v251, 12
	v_readlane_b32 s63, v251, 13
	v_readlane_b32 s64, v251, 14
	v_readlane_b32 s65, v251, 15
	v_readlane_b32 s66, v251, 16
	v_readlane_b32 s67, v251, 17
	v_readlane_b32 s68, v251, 18
	v_readlane_b32 s69, v251, 19
	v_readlane_b32 s70, v251, 20
	v_readlane_b32 s71, v251, 21
	s_mov_b64 s[2:3], s[60:61]
	s_cbranch_execz .LBB0_94
	s_branch .LBB0_95
